# final candidate: attention DMA spread + O-rescale/attention packed f32 split + saddr GEMM DMAs + softmax VALU trims + pipelined G2 residual epilogue (with wait state after exec write)
# speedup vs baseline: 1.0073x; 1.0073x over previous
; __device__ __forceinline__ unsigned cvt_pk_bf16(float lo, float hi) { f32x2_t v = {lo, hi}; bf16x2_t b = __builtin_convertvector(v, bf16x2_t); return __builtin_bit_cast(unsigned, b); }
;     __device__ __forceinline__ void operator()(const Acc& acc, const Unit& u, int wr, int wc, int fr, int fq) const {
;         const int row0 = u.pm * BM + wr * 64 + fr, col0 = u.pn * BM + wc * 32 + 8 * fq;
; #pragma unroll
;         for (int ai = 0; ai < 2; ++ai)
; #pragma unroll
;             for (int m = 0; m < 4; ++m) {
;                 const int row = row0 + ai * HALF + m * 16; float sq = 0.f;
; #pragma unroll
;                 for (int bj = 0; bj < 2; ++bj) {
;                     const size_t off = (size_t)row * DM + col0 + bj * HALF;
;                     const f32x4 b0 = *(const f32x4*)(base + off), b1 = *(const f32x4*)(base + off + 4);
;                     const f32x4 x0 = b0 + acc[ai][bj][m][0] * alpha, x1 = b1 + acc[ai][bj][m][1] * alpha;
;                     __builtin_nontemporal_store(x0, (f32x4*)(out + off)); __builtin_nontemporal_store(x1, (f32x4*)(out + off + 4));
;                     sq += (x0[0] * x0[0] + x0[1] * x0[1]) + (x0[2] * x0[2] + x0[3] * x0[3]) + (x1[0] * x1[0] + x1[1] * x1[1]) + (x1[2] * x1[2] + x1[3] * x1[3]);
;                     if (xb) { u32x4 w; w.x = cvt_pk_bf16(x0[0], x0[1]); w.y = cvt_pk_bf16(x0[2], x0[3]); w.z = cvt_pk_bf16(x1[0], x1[1]); w.w = cvt_pk_bf16(x1[2], x1[3]); *(u32x4*)(xb + off) = w; }
;                 }
;                 sq += __shfl_xor(sq, 16); sq += __shfl_xor(sq, 32);
;                 if (fq == 0) unsafeAtomicAdd(ss + row, sq);
;             }
;     }
.LBB0_299:
	s_and_b64 vcc, exec, s[46:47]
	s_cbranch_vccz .Lg2_epi_old
	v_lshl_add_u32 v146, s31, 8, v154
	v_lshl_or_b32 v144, s33, 8, v156
	v_lshl_add_u32 v145, v146, 10, v144
	v_lshlrev_b32_e32 v144, 2, v145
	v_lshlrev_b32_e32 v145, 1, v145
	v_lshlrev_b32_e32 v146, 2, v146
	v_xor_b32_e32 v147, 16, v162
	v_lshlrev_b32_e32 v147, 2, v147
	v_xor_b32_e32 v148, 32, v162
	v_lshlrev_b32_e32 v148, 2, v148
	s_mov_b64 s[72:73], s[52:53]
	global_load_dwordx4 v[180:183], v144, s[72:73]
	global_load_dwordx4 v[184:187], v144, s[72:73] offset:16
	global_load_dwordx4 v[188:191], v144, s[72:73] offset:512
	global_load_dwordx4 v[192:195], v144, s[72:73] offset:528
	s_add_u32 s72, s52, 0x10000
	s_addc_u32 s73, s53, 0
	global_load_dwordx4 v[196:199], v144, s[72:73]
	global_load_dwordx4 v[200:203], v144, s[72:73] offset:16
	global_load_dwordx4 v[204:207], v144, s[72:73] offset:512
	global_load_dwordx4 v[208:211], v144, s[72:73] offset:528
	s_waitcnt vmcnt(4)
	v_fma_f32 v124, v124, 0.5, v180
	v_fma_f32 v125, v125, 0.5, v181
	v_fma_f32 v126, v126, 0.5, v182
	v_fma_f32 v127, v127, 0.5, v183
	v_fma_f32 v120, v120, 0.5, v184
	v_fma_f32 v121, v121, 0.5, v185
	v_fma_f32 v122, v122, 0.5, v186
	v_fma_f32 v123, v123, 0.5, v187
	v_fma_f32 v116, v116, 0.5, v188
	v_fma_f32 v117, v117, 0.5, v189
	v_fma_f32 v118, v118, 0.5, v190
	v_fma_f32 v119, v119, 0.5, v191
	v_fma_f32 v112, v112, 0.5, v192
	v_fma_f32 v113, v113, 0.5, v193
	v_fma_f32 v114, v114, 0.5, v194
	v_fma_f32 v115, v115, 0.5, v195
	s_add_u32 s72, s52, 0x20000
	s_addc_u32 s73, s53, 0
	global_load_dwordx4 v[212:215], v144, s[72:73]
	global_load_dwordx4 v[216:219], v144, s[72:73] offset:16
	global_load_dwordx4 v[220:223], v144, s[72:73] offset:512
	global_load_dwordx4 v[224:227], v144, s[72:73] offset:528
	s_mov_b64 s[74:75], s[90:91]
	global_store_dwordx4 v144, v[124:127], s[74:75] nt
	global_store_dwordx4 v144, v[120:123], s[74:75] offset:16 nt
	global_store_dwordx4 v144, v[116:119], s[74:75] offset:512 nt
	global_store_dwordx4 v144, v[112:115], s[74:75] offset:528 nt
	v_cvt_pk_bf16_f32 v232, v124, v125
	v_cvt_pk_bf16_f32 v233, v126, v127
	v_cvt_pk_bf16_f32 v234, v120, v121
	v_cvt_pk_bf16_f32 v235, v122, v123
	v_cvt_pk_bf16_f32 v236, v116, v117
	v_cvt_pk_bf16_f32 v237, v118, v119
	v_cvt_pk_bf16_f32 v238, v112, v113
	v_cvt_pk_bf16_f32 v239, v114, v115
	s_mov_b64 s[82:83], s[70:71]
	global_store_dwordx4 v145, v[232:235], s[82:83]
	global_store_dwordx4 v145, v[236:239], s[82:83] offset:256
	v_mul_f32_e32 v228, v125, v125
	v_fmac_f32_e32 v228, v124, v124
	v_mul_f32_e32 v229, v121, v121
	v_fmac_f32_e32 v229, v120, v120
	v_mul_f32_e32 v230, v117, v117
	v_fmac_f32_e32 v230, v116, v116
	v_mul_f32_e32 v231, v113, v113
	v_fmac_f32_e32 v231, v112, v112
	v_mul_f32_e32 v240, v127, v127
	v_fmac_f32_e32 v240, v126, v126
	v_mul_f32_e32 v241, v123, v123
	v_fmac_f32_e32 v241, v122, v122
	v_mul_f32_e32 v242, v119, v119
	v_fmac_f32_e32 v242, v118, v118
	v_mul_f32_e32 v243, v115, v115
	v_fmac_f32_e32 v243, v114, v114
	v_add_f32_e32 v228, v228, v240
	v_add_f32_e32 v229, v229, v241
	v_add_f32_e32 v230, v230, v242
	v_add_f32_e32 v231, v231, v243
	v_add_f32_e32 v228, v228, v229
	v_add_f32_e32 v230, v230, v231
	v_add_f32_e32 v228, v228, v230
	ds_bpermute_b32 v229, v147, v228
	s_waitcnt lgkmcnt(0)
	v_add_f32_e32 v228, v228, v229
	ds_bpermute_b32 v229, v148, v228
	s_waitcnt lgkmcnt(0)
	v_add_f32_e32 v228, v228, v229
	s_and_saveexec_b64 s[6:7], s[8:9]
	s_nop 1
	global_atomic_add_f32 v146, v228, s[44:45]
	s_mov_b64 exec, s[6:7]
	s_waitcnt vmcnt(11)
	v_fma_f32 v108, v108, 0.5, v196
	v_fma_f32 v109, v109, 0.5, v197
	v_fma_f32 v110, v110, 0.5, v198
	v_fma_f32 v111, v111, 0.5, v199
	v_fma_f32 v104, v104, 0.5, v200
	v_fma_f32 v105, v105, 0.5, v201
	v_fma_f32 v106, v106, 0.5, v202
	v_fma_f32 v107, v107, 0.5, v203
	v_fma_f32 v100, v100, 0.5, v204
	v_fma_f32 v101, v101, 0.5, v205
	v_fma_f32 v102, v102, 0.5, v206
	v_fma_f32 v103, v103, 0.5, v207
	v_fma_f32 v96, v96, 0.5, v208
	v_fma_f32 v97, v97, 0.5, v209
	v_fma_f32 v98, v98, 0.5, v210
	v_fma_f32 v99, v99, 0.5, v211
	s_add_u32 s72, s52, 0x30000
	s_addc_u32 s73, s53, 0
	global_load_dwordx4 v[180:183], v144, s[72:73]
	global_load_dwordx4 v[184:187], v144, s[72:73] offset:16
	global_load_dwordx4 v[188:191], v144, s[72:73] offset:512
	global_load_dwordx4 v[192:195], v144, s[72:73] offset:528
	s_add_u32 s74, s90, 0x10000
	s_addc_u32 s75, s91, 0
	global_store_dwordx4 v144, v[108:111], s[74:75] nt
	global_store_dwordx4 v144, v[104:107], s[74:75] offset:16 nt
	global_store_dwordx4 v144, v[100:103], s[74:75] offset:512 nt
	global_store_dwordx4 v144, v[96:99], s[74:75] offset:528 nt
	v_cvt_pk_bf16_f32 v232, v108, v109
	v_cvt_pk_bf16_f32 v233, v110, v111
	v_cvt_pk_bf16_f32 v234, v104, v105
	v_cvt_pk_bf16_f32 v235, v106, v107
	v_cvt_pk_bf16_f32 v236, v100, v101
	v_cvt_pk_bf16_f32 v237, v102, v103
	v_cvt_pk_bf16_f32 v238, v96, v97
	v_cvt_pk_bf16_f32 v239, v98, v99
	s_add_u32 s82, s70, 0x8000
	s_addc_u32 s83, s71, 0
	global_store_dwordx4 v145, v[232:235], s[82:83]
	global_store_dwordx4 v145, v[236:239], s[82:83] offset:256
	v_mul_f32_e32 v228, v109, v109
	v_fmac_f32_e32 v228, v108, v108
	v_mul_f32_e32 v229, v105, v105
	v_fmac_f32_e32 v229, v104, v104
	v_mul_f32_e32 v230, v101, v101
	v_fmac_f32_e32 v230, v100, v100
	v_mul_f32_e32 v231, v97, v97
	v_fmac_f32_e32 v231, v96, v96
	v_mul_f32_e32 v240, v111, v111
	v_fmac_f32_e32 v240, v110, v110
	v_mul_f32_e32 v241, v107, v107
	v_fmac_f32_e32 v241, v106, v106
	v_mul_f32_e32 v242, v103, v103
	v_fmac_f32_e32 v242, v102, v102
	v_mul_f32_e32 v243, v99, v99
	v_fmac_f32_e32 v243, v98, v98
	v_add_f32_e32 v228, v228, v240
	v_add_f32_e32 v229, v229, v241
	v_add_f32_e32 v230, v230, v242
	v_add_f32_e32 v231, v231, v243
	v_add_f32_e32 v228, v228, v229
	v_add_f32_e32 v230, v230, v231
	v_add_f32_e32 v228, v228, v230
	ds_bpermute_b32 v229, v147, v228
	s_waitcnt lgkmcnt(0)
; __device__ __forceinline__ unsigned cvt_pk_bf16(float lo, float hi) { f32x2_t v = {lo, hi}; bf16x2_t b = __builtin_convertvector(v, bf16x2_t); return __builtin_bit_cast(unsigned, b); }
;     __device__ __forceinline__ void operator()(const Acc& acc, const Unit& u, int wr, int wc, int fr, int fq) const {
;         const int row0 = u.pm * BM + wr * 64 + fr, col0 = u.pn * BM + wc * 32 + 8 * fq;
; #pragma unroll
;         for (int ai = 0; ai < 2; ++ai)
; #pragma unroll
;             for (int m = 0; m < 4; ++m) {
;                 const int row = row0 + ai * HALF + m * 16; float sq = 0.f;
; #pragma unroll
;                 for (int bj = 0; bj < 2; ++bj) {
;                     const size_t off = (size_t)row * DM + col0 + bj * HALF;
;                     const f32x4 b0 = *(const f32x4*)(base + off), b1 = *(const f32x4*)(base + off + 4);
;                     const f32x4 x0 = b0 + acc[ai][bj][m][0] * alpha, x1 = b1 + acc[ai][bj][m][1] * alpha;
;                     __builtin_nontemporal_store(x0, (f32x4*)(out + off)); __builtin_nontemporal_store(x1, (f32x4*)(out + off + 4));
;                     sq += (x0[0] * x0[0] + x0[1] * x0[1]) + (x0[2] * x0[2] + x0[3] * x0[3]) + (x1[0] * x1[0] + x1[1] * x1[1]) + (x1[2] * x1[2] + x1[3] * x1[3]);
;                     if (xb) { u32x4 w; w.x = cvt_pk_bf16(x0[0], x0[1]); w.y = cvt_pk_bf16(x0[2], x0[3]); w.z = cvt_pk_bf16(x1[0], x1[1]); w.w = cvt_pk_bf16(x1[2], x1[3]); *(u32x4*)(xb + off) = w; }
;                 }
;                 sq += __shfl_xor(sq, 16); sq += __shfl_xor(sq, 32);
;                 if (fq == 0) unsafeAtomicAdd(ss + row, sq);
;             }
;     }
	v_add_f32_e32 v228, v228, v229
	ds_bpermute_b32 v229, v148, v228
	s_waitcnt lgkmcnt(0)
	v_add_f32_e32 v228, v228, v229
	s_and_saveexec_b64 s[6:7], s[8:9]
	s_nop 1
	global_atomic_add_f32 v146, v228, s[44:45] offset:64
	s_mov_b64 exec, s[6:7]
	s_waitcnt vmcnt(18)
	v_fma_f32 v92, v92, 0.5, v212
	v_fma_f32 v93, v93, 0.5, v213
	v_fma_f32 v94, v94, 0.5, v214
	v_fma_f32 v95, v95, 0.5, v215
	v_fma_f32 v88, v88, 0.5, v216
	v_fma_f32 v89, v89, 0.5, v217
	v_fma_f32 v90, v90, 0.5, v218
	v_fma_f32 v91, v91, 0.5, v219
	v_fma_f32 v84, v84, 0.5, v220
	v_fma_f32 v85, v85, 0.5, v221
	v_fma_f32 v86, v86, 0.5, v222
	v_fma_f32 v87, v87, 0.5, v223
	v_fma_f32 v80, v80, 0.5, v224
	v_fma_f32 v81, v81, 0.5, v225
	v_fma_f32 v82, v82, 0.5, v226
	v_fma_f32 v83, v83, 0.5, v227
	s_add_u32 s72, s52, 0x80000
	s_addc_u32 s73, s53, 0
	global_load_dwordx4 v[196:199], v144, s[72:73]
	global_load_dwordx4 v[200:203], v144, s[72:73] offset:16
	global_load_dwordx4 v[204:207], v144, s[72:73] offset:512
	global_load_dwordx4 v[208:211], v144, s[72:73] offset:528
	s_add_u32 s74, s90, 0x20000
	s_addc_u32 s75, s91, 0
	global_store_dwordx4 v144, v[92:95], s[74:75] nt
	global_store_dwordx4 v144, v[88:91], s[74:75] offset:16 nt
	global_store_dwordx4 v144, v[84:87], s[74:75] offset:512 nt
	global_store_dwordx4 v144, v[80:83], s[74:75] offset:528 nt
	v_cvt_pk_bf16_f32 v232, v92, v93
	v_cvt_pk_bf16_f32 v233, v94, v95
	v_cvt_pk_bf16_f32 v234, v88, v89
	v_cvt_pk_bf16_f32 v235, v90, v91
	v_cvt_pk_bf16_f32 v236, v84, v85
	v_cvt_pk_bf16_f32 v237, v86, v87
	v_cvt_pk_bf16_f32 v238, v80, v81
	v_cvt_pk_bf16_f32 v239, v82, v83
	s_add_u32 s82, s70, 0x10000
	s_addc_u32 s83, s71, 0
	global_store_dwordx4 v145, v[232:235], s[82:83]
	global_store_dwordx4 v145, v[236:239], s[82:83] offset:256
	v_mul_f32_e32 v228, v93, v93
	v_fmac_f32_e32 v228, v92, v92
	v_mul_f32_e32 v229, v89, v89
	v_fmac_f32_e32 v229, v88, v88
	v_mul_f32_e32 v230, v85, v85
	v_fmac_f32_e32 v230, v84, v84
	v_mul_f32_e32 v231, v81, v81
	v_fmac_f32_e32 v231, v80, v80
	v_mul_f32_e32 v240, v95, v95
	v_fmac_f32_e32 v240, v94, v94
	v_mul_f32_e32 v241, v91, v91
	v_fmac_f32_e32 v241, v90, v90
	v_mul_f32_e32 v242, v87, v87
	v_fmac_f32_e32 v242, v86, v86
	v_mul_f32_e32 v243, v83, v83
	v_fmac_f32_e32 v243, v82, v82
	v_add_f32_e32 v228, v228, v240
	v_add_f32_e32 v229, v229, v241
	v_add_f32_e32 v230, v230, v242
	v_add_f32_e32 v231, v231, v243
	v_add_f32_e32 v228, v228, v229
	v_add_f32_e32 v230, v230, v231
	v_add_f32_e32 v228, v228, v230
	ds_bpermute_b32 v229, v147, v228
	s_waitcnt lgkmcnt(0)
	v_add_f32_e32 v228, v228, v229
	ds_bpermute_b32 v229, v148, v228
	s_waitcnt lgkmcnt(0)
	v_add_f32_e32 v228, v228, v229
	s_and_saveexec_b64 s[6:7], s[8:9]
	s_nop 1
	global_atomic_add_f32 v146, v228, s[44:45] offset:128
	s_mov_b64 exec, s[6:7]
	s_waitcnt vmcnt(18)
	v_fma_f32 v76, v76, 0.5, v180
	v_fma_f32 v77, v77, 0.5, v181
	v_fma_f32 v78, v78, 0.5, v182
	v_fma_f32 v79, v79, 0.5, v183
	v_fma_f32 v72, v72, 0.5, v184
	v_fma_f32 v73, v73, 0.5, v185
	v_fma_f32 v74, v74, 0.5, v186
	v_fma_f32 v75, v75, 0.5, v187
	v_fma_f32 v68, v68, 0.5, v188
	v_fma_f32 v69, v69, 0.5, v189
	v_fma_f32 v70, v70, 0.5, v190
	v_fma_f32 v71, v71, 0.5, v191
	v_fma_f32 v64, v64, 0.5, v192
	v_fma_f32 v65, v65, 0.5, v193
	v_fma_f32 v66, v66, 0.5, v194
	v_fma_f32 v67, v67, 0.5, v195
	s_add_u32 s72, s52, 0x90000
	s_addc_u32 s73, s53, 0
	global_load_dwordx4 v[212:215], v144, s[72:73]
	global_load_dwordx4 v[216:219], v144, s[72:73] offset:16
	global_load_dwordx4 v[220:223], v144, s[72:73] offset:512
	global_load_dwordx4 v[224:227], v144, s[72:73] offset:528
	s_add_u32 s74, s90, 0x30000
	s_addc_u32 s75, s91, 0
	global_store_dwordx4 v144, v[76:79], s[74:75] nt
	global_store_dwordx4 v144, v[72:75], s[74:75] offset:16 nt
	global_store_dwordx4 v144, v[68:71], s[74:75] offset:512 nt
	global_store_dwordx4 v144, v[64:67], s[74:75] offset:528 nt
	v_cvt_pk_bf16_f32 v232, v76, v77
	v_cvt_pk_bf16_f32 v233, v78, v79
	v_cvt_pk_bf16_f32 v234, v72, v73
	v_cvt_pk_bf16_f32 v235, v74, v75
	v_cvt_pk_bf16_f32 v236, v68, v69
	v_cvt_pk_bf16_f32 v237, v70, v71
	v_cvt_pk_bf16_f32 v238, v64, v65
	v_cvt_pk_bf16_f32 v239, v66, v67
	s_add_u32 s82, s70, 0x18000
	s_addc_u32 s83, s71, 0
	global_store_dwordx4 v145, v[232:235], s[82:83]
	global_store_dwordx4 v145, v[236:239], s[82:83] offset:256
	v_mul_f32_e32 v228, v77, v77
	v_fmac_f32_e32 v228, v76, v76
	v_mul_f32_e32 v229, v73, v73
	v_fmac_f32_e32 v229, v72, v72
	v_mul_f32_e32 v230, v69, v69
	v_fmac_f32_e32 v230, v68, v68
	v_mul_f32_e32 v231, v65, v65
	v_fmac_f32_e32 v231, v64, v64
	v_mul_f32_e32 v240, v79, v79
	v_fmac_f32_e32 v240, v78, v78
	v_mul_f32_e32 v241, v75, v75
	v_fmac_f32_e32 v241, v74, v74
	v_mul_f32_e32 v242, v71, v71
	v_fmac_f32_e32 v242, v70, v70
	v_mul_f32_e32 v243, v67, v67
	v_fmac_f32_e32 v243, v66, v66
	v_add_f32_e32 v228, v228, v240
	v_add_f32_e32 v229, v229, v241
	v_add_f32_e32 v230, v230, v242
	v_add_f32_e32 v231, v231, v243
	v_add_f32_e32 v228, v228, v229
	v_add_f32_e32 v230, v230, v231
	v_add_f32_e32 v228, v228, v230
	ds_bpermute_b32 v229, v147, v228
	s_waitcnt lgkmcnt(0)
	v_add_f32_e32 v228, v228, v229
	ds_bpermute_b32 v229, v148, v228
	s_waitcnt lgkmcnt(0)
	v_add_f32_e32 v228, v228, v229
	s_and_saveexec_b64 s[6:7], s[8:9]
	s_nop 1
	global_atomic_add_f32 v146, v228, s[44:45] offset:192
	s_mov_b64 exec, s[6:7]
	s_waitcnt vmcnt(18)
; __device__ __forceinline__ unsigned cvt_pk_bf16(float lo, float hi) { f32x2_t v = {lo, hi}; bf16x2_t b = __builtin_convertvector(v, bf16x2_t); return __builtin_bit_cast(unsigned, b); }
;     __device__ __forceinline__ void operator()(const Acc& acc, const Unit& u, int wr, int wc, int fr, int fq) const {
;         const int row0 = u.pm * BM + wr * 64 + fr, col0 = u.pn * BM + wc * 32 + 8 * fq;
; #pragma unroll
;         for (int ai = 0; ai < 2; ++ai)
; #pragma unroll
;             for (int m = 0; m < 4; ++m) {
;                 const int row = row0 + ai * HALF + m * 16; float sq = 0.f;
; #pragma unroll
;                 for (int bj = 0; bj < 2; ++bj) {
;                     const size_t off = (size_t)row * DM + col0 + bj * HALF;
;                     const f32x4 b0 = *(const f32x4*)(base + off), b1 = *(const f32x4*)(base + off + 4);
;                     const f32x4 x0 = b0 + acc[ai][bj][m][0] * alpha, x1 = b1 + acc[ai][bj][m][1] * alpha;
;                     __builtin_nontemporal_store(x0, (f32x4*)(out + off)); __builtin_nontemporal_store(x1, (f32x4*)(out + off + 4));
;                     sq += (x0[0] * x0[0] + x0[1] * x0[1]) + (x0[2] * x0[2] + x0[3] * x0[3]) + (x1[0] * x1[0] + x1[1] * x1[1]) + (x1[2] * x1[2] + x1[3] * x1[3]);
;                     if (xb) { u32x4 w; w.x = cvt_pk_bf16(x0[0], x0[1]); w.y = cvt_pk_bf16(x0[2], x0[3]); w.z = cvt_pk_bf16(x1[0], x1[1]); w.w = cvt_pk_bf16(x1[2], x1[3]); *(u32x4*)(xb + off) = w; }
;                 }
;                 sq += __shfl_xor(sq, 16); sq += __shfl_xor(sq, 32);
;                 if (fq == 0) unsafeAtomicAdd(ss + row, sq);
;             }
;     }
	v_fma_f32 v60, v60, 0.5, v196
	v_fma_f32 v61, v61, 0.5, v197
	v_fma_f32 v62, v62, 0.5, v198
	v_fma_f32 v63, v63, 0.5, v199
	v_fma_f32 v56, v56, 0.5, v200
	v_fma_f32 v57, v57, 0.5, v201
	v_fma_f32 v58, v58, 0.5, v202
	v_fma_f32 v59, v59, 0.5, v203
	v_fma_f32 v52, v52, 0.5, v204
	v_fma_f32 v53, v53, 0.5, v205
	v_fma_f32 v54, v54, 0.5, v206
	v_fma_f32 v55, v55, 0.5, v207
	v_fma_f32 v48, v48, 0.5, v208
	v_fma_f32 v49, v49, 0.5, v209
	v_fma_f32 v50, v50, 0.5, v210
	v_fma_f32 v51, v51, 0.5, v211
	s_add_u32 s72, s52, 0xa0000
	s_addc_u32 s73, s53, 0
	global_load_dwordx4 v[180:183], v144, s[72:73]
	global_load_dwordx4 v[184:187], v144, s[72:73] offset:16
	global_load_dwordx4 v[188:191], v144, s[72:73] offset:512
	global_load_dwordx4 v[192:195], v144, s[72:73] offset:528
	s_add_u32 s74, s90, 0x80000
	s_addc_u32 s75, s91, 0
	global_store_dwordx4 v144, v[60:63], s[74:75] nt
	global_store_dwordx4 v144, v[56:59], s[74:75] offset:16 nt
	global_store_dwordx4 v144, v[52:55], s[74:75] offset:512 nt
	global_store_dwordx4 v144, v[48:51], s[74:75] offset:528 nt
	v_cvt_pk_bf16_f32 v232, v60, v61
	v_cvt_pk_bf16_f32 v233, v62, v63
	v_cvt_pk_bf16_f32 v234, v56, v57
	v_cvt_pk_bf16_f32 v235, v58, v59
	v_cvt_pk_bf16_f32 v236, v52, v53
	v_cvt_pk_bf16_f32 v237, v54, v55
	v_cvt_pk_bf16_f32 v238, v48, v49
	v_cvt_pk_bf16_f32 v239, v50, v51
	s_add_u32 s82, s70, 0x40000
	s_addc_u32 s83, s71, 0
	global_store_dwordx4 v145, v[232:235], s[82:83]
	global_store_dwordx4 v145, v[236:239], s[82:83] offset:256
	v_mul_f32_e32 v228, v61, v61
	v_fmac_f32_e32 v228, v60, v60
	v_mul_f32_e32 v229, v57, v57
	v_fmac_f32_e32 v229, v56, v56
	v_mul_f32_e32 v230, v53, v53
	v_fmac_f32_e32 v230, v52, v52
	v_mul_f32_e32 v231, v49, v49
	v_fmac_f32_e32 v231, v48, v48
	v_mul_f32_e32 v240, v63, v63
	v_fmac_f32_e32 v240, v62, v62
	v_mul_f32_e32 v241, v59, v59
	v_fmac_f32_e32 v241, v58, v58
	v_mul_f32_e32 v242, v55, v55
	v_fmac_f32_e32 v242, v54, v54
	v_mul_f32_e32 v243, v51, v51
	v_fmac_f32_e32 v243, v50, v50
	v_add_f32_e32 v228, v228, v240
	v_add_f32_e32 v229, v229, v241
	v_add_f32_e32 v230, v230, v242
	v_add_f32_e32 v231, v231, v243
	v_add_f32_e32 v228, v228, v229
	v_add_f32_e32 v230, v230, v231
	v_add_f32_e32 v228, v228, v230
	ds_bpermute_b32 v229, v147, v228
	s_waitcnt lgkmcnt(0)
	v_add_f32_e32 v228, v228, v229
	ds_bpermute_b32 v229, v148, v228
	s_waitcnt lgkmcnt(0)
	v_add_f32_e32 v228, v228, v229
	s_and_saveexec_b64 s[6:7], s[8:9]
	s_nop 1
	global_atomic_add_f32 v146, v228, s[44:45] offset:512
	s_mov_b64 exec, s[6:7]
	s_waitcnt vmcnt(18)
	v_fma_f32 v44, v44, 0.5, v212
	v_fma_f32 v45, v45, 0.5, v213
	v_fma_f32 v46, v46, 0.5, v214
	v_fma_f32 v47, v47, 0.5, v215
	v_fma_f32 v40, v40, 0.5, v216
	v_fma_f32 v41, v41, 0.5, v217
	v_fma_f32 v42, v42, 0.5, v218
	v_fma_f32 v43, v43, 0.5, v219
	v_fma_f32 v36, v36, 0.5, v220
	v_fma_f32 v37, v37, 0.5, v221
	v_fma_f32 v38, v38, 0.5, v222
	v_fma_f32 v39, v39, 0.5, v223
	v_fma_f32 v32, v32, 0.5, v224
	v_fma_f32 v33, v33, 0.5, v225
	v_fma_f32 v34, v34, 0.5, v226
	v_fma_f32 v35, v35, 0.5, v227
	s_add_u32 s72, s52, 0xb0000
	s_addc_u32 s73, s53, 0
	global_load_dwordx4 v[196:199], v144, s[72:73]
	global_load_dwordx4 v[200:203], v144, s[72:73] offset:16
	global_load_dwordx4 v[204:207], v144, s[72:73] offset:512
	global_load_dwordx4 v[208:211], v144, s[72:73] offset:528
	s_add_u32 s74, s90, 0x90000
	s_addc_u32 s75, s91, 0
	global_store_dwordx4 v144, v[44:47], s[74:75] nt
	global_store_dwordx4 v144, v[40:43], s[74:75] offset:16 nt
	global_store_dwordx4 v144, v[36:39], s[74:75] offset:512 nt
	global_store_dwordx4 v144, v[32:35], s[74:75] offset:528 nt
	v_cvt_pk_bf16_f32 v232, v44, v45
	v_cvt_pk_bf16_f32 v233, v46, v47
	v_cvt_pk_bf16_f32 v234, v40, v41
	v_cvt_pk_bf16_f32 v235, v42, v43
	v_cvt_pk_bf16_f32 v236, v36, v37
	v_cvt_pk_bf16_f32 v237, v38, v39
	v_cvt_pk_bf16_f32 v238, v32, v33
	v_cvt_pk_bf16_f32 v239, v34, v35
	s_add_u32 s82, s70, 0x48000
	s_addc_u32 s83, s71, 0
	global_store_dwordx4 v145, v[232:235], s[82:83]
	global_store_dwordx4 v145, v[236:239], s[82:83] offset:256
	v_mul_f32_e32 v228, v45, v45
	v_fmac_f32_e32 v228, v44, v44
	v_mul_f32_e32 v229, v41, v41
	v_fmac_f32_e32 v229, v40, v40
	v_mul_f32_e32 v230, v37, v37
	v_fmac_f32_e32 v230, v36, v36
	v_mul_f32_e32 v231, v33, v33
	v_fmac_f32_e32 v231, v32, v32
	v_mul_f32_e32 v240, v47, v47
	v_fmac_f32_e32 v240, v46, v46
	v_mul_f32_e32 v241, v43, v43
	v_fmac_f32_e32 v241, v42, v42
	v_mul_f32_e32 v242, v39, v39
	v_fmac_f32_e32 v242, v38, v38
	v_mul_f32_e32 v243, v35, v35
	v_fmac_f32_e32 v243, v34, v34
	v_add_f32_e32 v228, v228, v240
	v_add_f32_e32 v229, v229, v241
	v_add_f32_e32 v230, v230, v242
	v_add_f32_e32 v231, v231, v243
	v_add_f32_e32 v228, v228, v229
	v_add_f32_e32 v230, v230, v231
	v_add_f32_e32 v228, v228, v230
	ds_bpermute_b32 v229, v147, v228
	s_waitcnt lgkmcnt(0)
; __device__ __forceinline__ unsigned cvt_pk_bf16(float lo, float hi) { f32x2_t v = {lo, hi}; bf16x2_t b = __builtin_convertvector(v, bf16x2_t); return __builtin_bit_cast(unsigned, b); }
;     __device__ __forceinline__ void operator()(const Acc& acc, const Unit& u, int wr, int wc, int fr, int fq) const {
;         const int row0 = u.pm * BM + wr * 64 + fr, col0 = u.pn * BM + wc * 32 + 8 * fq;
; #pragma unroll
;         for (int ai = 0; ai < 2; ++ai)
; #pragma unroll
;             for (int m = 0; m < 4; ++m) {
;                 const int row = row0 + ai * HALF + m * 16; float sq = 0.f;
; #pragma unroll
;                 for (int bj = 0; bj < 2; ++bj) {
;                     const size_t off = (size_t)row * DM + col0 + bj * HALF;
;                     const f32x4 b0 = *(const f32x4*)(base + off), b1 = *(const f32x4*)(base + off + 4);
;                     const f32x4 x0 = b0 + acc[ai][bj][m][0] * alpha, x1 = b1 + acc[ai][bj][m][1] * alpha;
;                     __builtin_nontemporal_store(x0, (f32x4*)(out + off)); __builtin_nontemporal_store(x1, (f32x4*)(out + off + 4));
;                     sq += (x0[0] * x0[0] + x0[1] * x0[1]) + (x0[2] * x0[2] + x0[3] * x0[3]) + (x1[0] * x1[0] + x1[1] * x1[1]) + (x1[2] * x1[2] + x1[3] * x1[3]);
;                     if (xb) { u32x4 w; w.x = cvt_pk_bf16(x0[0], x0[1]); w.y = cvt_pk_bf16(x0[2], x0[3]); w.z = cvt_pk_bf16(x1[0], x1[1]); w.w = cvt_pk_bf16(x1[2], x1[3]); *(u32x4*)(xb + off) = w; }
;                 }
;                 sq += __shfl_xor(sq, 16); sq += __shfl_xor(sq, 32);
;                 if (fq == 0) unsafeAtomicAdd(ss + row, sq);
;             }
;     }
	v_add_f32_e32 v228, v228, v229
	ds_bpermute_b32 v229, v148, v228
	s_waitcnt lgkmcnt(0)
	v_add_f32_e32 v228, v228, v229
	s_and_saveexec_b64 s[6:7], s[8:9]
	s_nop 1
	global_atomic_add_f32 v146, v228, s[44:45] offset:576
	s_mov_b64 exec, s[6:7]
	s_waitcnt vmcnt(18)
	v_fma_f32 v28, v28, 0.5, v180
	v_fma_f32 v29, v29, 0.5, v181
	v_fma_f32 v30, v30, 0.5, v182
	v_fma_f32 v31, v31, 0.5, v183
	v_fma_f32 v24, v24, 0.5, v184
	v_fma_f32 v25, v25, 0.5, v185
	v_fma_f32 v26, v26, 0.5, v186
	v_fma_f32 v27, v27, 0.5, v187
	v_fma_f32 v20, v20, 0.5, v188
	v_fma_f32 v21, v21, 0.5, v189
	v_fma_f32 v22, v22, 0.5, v190
	v_fma_f32 v23, v23, 0.5, v191
	v_fma_f32 v16, v16, 0.5, v192
	v_fma_f32 v17, v17, 0.5, v193
	v_fma_f32 v18, v18, 0.5, v194
	v_fma_f32 v19, v19, 0.5, v195
	s_add_u32 s74, s90, 0xa0000
	s_addc_u32 s75, s91, 0
	global_store_dwordx4 v144, v[28:31], s[74:75] nt
	global_store_dwordx4 v144, v[24:27], s[74:75] offset:16 nt
	global_store_dwordx4 v144, v[20:23], s[74:75] offset:512 nt
	global_store_dwordx4 v144, v[16:19], s[74:75] offset:528 nt
	v_cvt_pk_bf16_f32 v232, v28, v29
	v_cvt_pk_bf16_f32 v233, v30, v31
	v_cvt_pk_bf16_f32 v234, v24, v25
	v_cvt_pk_bf16_f32 v235, v26, v27
	v_cvt_pk_bf16_f32 v236, v20, v21
	v_cvt_pk_bf16_f32 v237, v22, v23
	v_cvt_pk_bf16_f32 v238, v16, v17
	v_cvt_pk_bf16_f32 v239, v18, v19
	s_add_u32 s82, s70, 0x50000
	s_addc_u32 s83, s71, 0
	global_store_dwordx4 v145, v[232:235], s[82:83]
	global_store_dwordx4 v145, v[236:239], s[82:83] offset:256
	v_mul_f32_e32 v228, v29, v29
	v_fmac_f32_e32 v228, v28, v28
	v_mul_f32_e32 v229, v25, v25
	v_fmac_f32_e32 v229, v24, v24
	v_mul_f32_e32 v230, v21, v21
	v_fmac_f32_e32 v230, v20, v20
	v_mul_f32_e32 v231, v17, v17
	v_fmac_f32_e32 v231, v16, v16
	v_mul_f32_e32 v240, v31, v31
	v_fmac_f32_e32 v240, v30, v30
	v_mul_f32_e32 v241, v27, v27
	v_fmac_f32_e32 v241, v26, v26
	v_mul_f32_e32 v242, v23, v23
	v_fmac_f32_e32 v242, v22, v22
	v_mul_f32_e32 v243, v19, v19
	v_fmac_f32_e32 v243, v18, v18
	v_add_f32_e32 v228, v228, v240
	v_add_f32_e32 v229, v229, v241
	v_add_f32_e32 v230, v230, v242
	v_add_f32_e32 v231, v231, v243
	v_add_f32_e32 v228, v228, v229
	v_add_f32_e32 v230, v230, v231
	v_add_f32_e32 v228, v228, v230
	ds_bpermute_b32 v229, v147, v228
	s_waitcnt lgkmcnt(0)
	v_add_f32_e32 v228, v228, v229
	ds_bpermute_b32 v229, v148, v228
	s_waitcnt lgkmcnt(0)
	v_add_f32_e32 v228, v228, v229
	s_and_saveexec_b64 s[6:7], s[8:9]
	s_nop 1
	global_atomic_add_f32 v146, v228, s[44:45] offset:640
	s_mov_b64 exec, s[6:7]
	s_waitcnt vmcnt(14)
	v_fma_f32 v12, v12, 0.5, v196
	v_fma_f32 v13, v13, 0.5, v197
	v_fma_f32 v14, v14, 0.5, v198
	v_fma_f32 v15, v15, 0.5, v199
	v_fma_f32 v8, v8, 0.5, v200
	v_fma_f32 v9, v9, 0.5, v201
	v_fma_f32 v10, v10, 0.5, v202
	v_fma_f32 v11, v11, 0.5, v203
	v_fma_f32 v4, v4, 0.5, v204
	v_fma_f32 v5, v5, 0.5, v205
	v_fma_f32 v6, v6, 0.5, v206
	v_fma_f32 v7, v7, 0.5, v207
	v_fma_f32 v0, v0, 0.5, v208
	v_fma_f32 v1, v1, 0.5, v209
	v_fma_f32 v2, v2, 0.5, v210
	v_fma_f32 v3, v3, 0.5, v211
	s_add_u32 s74, s90, 0xb0000
	s_addc_u32 s75, s91, 0
	global_store_dwordx4 v144, v[12:15], s[74:75] nt
	global_store_dwordx4 v144, v[8:11], s[74:75] offset:16 nt
	global_store_dwordx4 v144, v[4:7], s[74:75] offset:512 nt
	global_store_dwordx4 v144, v[0:3], s[74:75] offset:528 nt
	v_cvt_pk_bf16_f32 v232, v12, v13
	v_cvt_pk_bf16_f32 v233, v14, v15
	v_cvt_pk_bf16_f32 v234, v8, v9
	v_cvt_pk_bf16_f32 v235, v10, v11
	v_cvt_pk_bf16_f32 v236, v4, v5
	v_cvt_pk_bf16_f32 v237, v6, v7
	v_cvt_pk_bf16_f32 v238, v0, v1
	v_cvt_pk_bf16_f32 v239, v2, v3
	s_add_u32 s82, s70, 0x58000
	s_addc_u32 s83, s71, 0
	global_store_dwordx4 v145, v[232:235], s[82:83]
	global_store_dwordx4 v145, v[236:239], s[82:83] offset:256
	v_mul_f32_e32 v228, v13, v13
	v_fmac_f32_e32 v228, v12, v12
	v_mul_f32_e32 v229, v9, v9
	v_fmac_f32_e32 v229, v8, v8
	v_mul_f32_e32 v230, v5, v5
	v_fmac_f32_e32 v230, v4, v4
	v_mul_f32_e32 v231, v1, v1
	v_fmac_f32_e32 v231, v0, v0
	v_mul_f32_e32 v240, v15, v15
	v_fmac_f32_e32 v240, v14, v14
	v_mul_f32_e32 v241, v11, v11
	v_fmac_f32_e32 v241, v10, v10
	v_mul_f32_e32 v242, v7, v7
	v_fmac_f32_e32 v242, v6, v6
	v_mul_f32_e32 v243, v3, v3
	v_fmac_f32_e32 v243, v2, v2
	v_add_f32_e32 v228, v228, v240
	v_add_f32_e32 v229, v229, v241
	v_add_f32_e32 v230, v230, v242
	v_add_f32_e32 v231, v231, v243
	v_add_f32_e32 v228, v228, v229
	v_add_f32_e32 v230, v230, v231
	v_add_f32_e32 v228, v228, v230
	ds_bpermute_b32 v229, v147, v228
	s_waitcnt lgkmcnt(0)
	v_add_f32_e32 v228, v228, v229
	ds_bpermute_b32 v229, v148, v228
	s_waitcnt lgkmcnt(0)
	v_add_f32_e32 v228, v228, v229
	s_and_saveexec_b64 s[6:7], s[8:9]
	s_nop 1
	global_atomic_add_f32 v146, v228, s[44:45] offset:704
	s_mov_b64 exec, s[6:7]
	s_branch .Lg2_epi_done
